# gather phase: next token's prologue loads (indices, x row, scores, scale words) issued inside the current token's epilogue
# speedup vs baseline: 1.0068x; 1.0007x over previous
.LBB0_1058:
	s_or_b64 exec, exec, s[0:1]
	s_waitcnt lgkmcnt(0)
	s_barrier
	s_and_saveexec_b64 s[0:1], s[52:53]
	s_cbranch_execz .LBB0_1067
	v_and_b32_e32 v2, 8, v130
	v_cmp_eq_u32_e64 s[0:1], 0, v2
	v_and_b32_e32 v2, 4, v130
	v_readlane_b32 s12, v247, 2
	v_cmp_eq_u32_e64 s[2:3], 0, v2
	v_and_b32_e32 v2, 2, v130
	v_readlane_b32 s13, v247, 3
	v_readlane_b32 s15, v247, 5
	v_cmp_eq_u32_e64 s[4:5], 0, v2
	v_and_b32_e32 v2, 1, v130
	v_cmp_lt_i32_e32 vcc, v81, v83
	v_readlane_b32 s16, v247, 6
	s_and_b32 s13, s13, 0xffff
	s_and_b32 s15, s15, 0xffff
	v_mov_b32_e32 v77, 0
	v_cmp_eq_u32_e64 s[6:7], 0, v2
	v_cndmask_b32_e32 v2, v75, v81, vcc
	v_cmp_lt_i32_e32 vcc, v154, v83
	v_readlane_b32 s36, v247, 61
	s_mov_b32 s11, 0x20000
	s_mov_b32 s10, 0x800000
	v_readlane_b32 s14, v247, 4
	v_readlane_b32 s17, v247, 7
	v_readlane_b32 s18, v247, 8
	v_readlane_b32 s19, v247, 9
	s_add_u32 s16, s74, 0x1000000
	v_lshlrev_b32_e32 v0, 1, v74
	v_mov_b32_e32 v1, v77
	v_lshlrev_b32_e32 v73, 2, v2
	v_cndmask_b32_e32 v2, v75, v154, vcc
	v_readlane_b32 s44, v248, 5
	v_readlane_b32 s45, v248, 6
	s_addc_u32 s17, s75, 0
	v_lshl_add_u64 v[0:1], s[68:69], 0, v[0:1]
	v_lshlrev_b32_e32 v82, 2, v2
	v_lshl_add_u64 v[2:3], s[44:45], 0, v[76:77]
	v_or_b32_e32 v83, v79, v137
	s_mov_b64 s[18:19], 0
	s_mov_b32 s8, s12
	s_mov_b32 s9, s13
	s_mov_b32 s12, s14
	s_mov_b32 s13, s15
	s_mov_b32 s14, s10
	s_mov_b32 s15, s11
	s_mov_b32 s24, 0x378e98ab
	s_mov_b32 s25, 0x3b7cd369
	s_mov_b32 s26, 0xbcc618b2
	s_mov_b32 s27, 0x3dda74e4
	s_mov_b32 s28, 0x3f228afd
	s_mov_b32 s29, 0x3e03c728
	s_mov_b32 s30, 0xbfb8aa3b
	s_mov_b32 s31, 0x42ce8ed0
	s_mov_b32 s33, 0xc2b17218
	v_mov_b32_e32 v84, 0x3ba10414
	s_brev_b32 s34, -2
	s_mov_b64 s[20:21], 0x5000
	s_movk_i32 s35, 0x5000
	s_movk_i32 s36, 0x7fff
	v_mov_b32_e32 v85, 0xb9c68948
	v_mov_b32_e32 v86, 0x7f800000
	v_readlane_b32 s37, v247, 62
	v_readlane_b32 s38, v247, 63
	v_readlane_b32 s39, v248, 0
	v_readlane_b32 s40, v248, 1
	v_readlane_b32 s41, v248, 2
	v_readlane_b32 s42, v248, 3
	v_readlane_b32 s43, v248, 4
	v_readlane_b32 s46, v248, 7
	v_readlane_b32 s47, v248, 8
	v_readlane_b32 s48, v248, 9
	v_readlane_b32 s49, v248, 10
	v_readlane_b32 s50, v248, 11
	v_readlane_b32 s51, v248, 12
	v_min_i32_e32 v176, 0x7fff, v132
	v_ashrrev_i32_e32 v177, 31, v176
	v_lshlrev_b64 v[178:179], 9, v[176:177]
	v_lshl_or_b32 v178, v128, 2, v178
	v_lshl_add_u64 v[180:181], s[74:75], 0, v[178:179]
	global_load_dword v160, v[180:181], off
	global_load_dword v162, v[180:181], off offset:256
	v_lshlrev_b64 v[180:181], 11, v[176:177]
	v_lshl_add_u64 v[180:181], v[0:1], 0, v[180:181]
	global_load_dwordx4 v[164:167], v[180:181], off
	global_load_dwordx4 v[168:171], v[180:181], off offset:16
	v_lshl_add_u64 v[180:181], s[16:17], 0, v[178:179]
	v_or_b32_e32 v178, 0x100, v178
	v_lshl_add_u64 v[178:179], s[16:17], 0, v[178:179]
	global_load_dword v172, v[180:181], off
	global_load_dword v173, v[178:179], off
	s_waitcnt vmcnt(0)
	v_ashrrev_i32_e32 v161, 31, v160
	v_ashrrev_i32_e32 v163, 31, v162
	v_lshlrev_b64 v[176:177], 2, v[160:161]
	v_lshlrev_b64 v[178:179], 2, v[162:163]
	v_lshl_add_u64 v[180:181], s[54:55], 0, v[176:177]
	v_lshl_add_u64 v[176:177], s[56:57], 0, v[176:177]
	v_lshl_add_u64 v[182:183], s[54:55], 0, v[178:179]
	v_lshl_add_u64 v[178:179], s[56:57], 0, v[178:179]
	global_load_dword v174, v[176:177], off
	global_load_dword v175, v[178:179], off
	global_load_dword v161, v[180:181], off
	global_load_dword v163, v[182:183], off
	s_waitcnt vmcnt(0)
	s_branch .LBB0_1061
.LBB0_1060:
	v_ashrrev_i32_e32 v4, 11, v132
	v_mul_i32_i24_e32 v4, 0x1800, v4
	v_readlane_b32 s76, v248, 40
	v_ashrrev_i32_e32 v5, 31, v4
	v_readlane_b32 s90, v248, 54
	v_readlane_b32 s91, v248, 55
	v_lshl_add_u64 v[18:19], v[8:9], 2, v[2:3]
	v_add_u32_e32 v132, s62, v132
	v_lshl_add_u64 v[4:5], v[4:5], 2, s[90:91]
	v_lshl_add_u64 v[16:17], v[4:5], 0, v[76:77]
	v_add_co_u32_e32 v20, vcc, s35, v16
	v_readlane_b32 s77, v248, 41
	s_nop 0
	v_addc_co_u32_e32 v21, vcc, 0, v17, vcc
	v_min_i32_e32 v176, 0x7fff, v132
	v_ashrrev_i32_e32 v177, 31, v176
	v_lshlrev_b64 v[178:179], 9, v[176:177]
	v_lshl_or_b32 v178, v128, 2, v178
	v_lshl_add_u64 v[180:181], s[74:75], 0, v[178:179]
	global_load_dword v160, v[180:181], off
	global_load_dword v162, v[180:181], off offset:256
	v_lshlrev_b64 v[180:181], 11, v[176:177]
	v_lshl_add_u64 v[180:181], v[0:1], 0, v[180:181]
	global_load_dwordx4 v[164:167], v[180:181], off
	global_load_dwordx4 v[168:171], v[180:181], off offset:16
	v_lshl_add_u64 v[180:181], s[16:17], 0, v[178:179]
	v_or_b32_e32 v178, 0x100, v178
	v_lshl_add_u64 v[178:179], s[16:17], 0, v[178:179]
	global_load_dword v172, v[180:181], off
	global_load_dword v173, v[178:179], off
	global_load_dwordx4 v[4:7], v[20:21], off
	global_load_dwordx4 v[8:11], v[18:19], off
	global_load_dwordx4 v[12:15], v[18:19], off offset:16
	v_lshl_add_u64 v[16:17], v[16:17], 0, s[20:21]
	v_cmp_lt_i32_e32 vcc, s36, v132
	s_or_b64 s[18:19], vcc, s[18:19]
	v_readlane_b32 s78, v248, 42
	v_readlane_b32 s79, v248, 43
	v_readlane_b32 s80, v248, 44
	v_readlane_b32 s81, v248, 45
	v_readlane_b32 s82, v248, 46
	v_readlane_b32 s83, v248, 47
	v_readlane_b32 s84, v248, 48
	v_readlane_b32 s85, v248, 49
	v_readlane_b32 s86, v248, 50
	v_readlane_b32 s87, v248, 51
	v_readlane_b32 s88, v248, 52
	v_readlane_b32 s89, v248, 53
	s_waitcnt vmcnt(1)
	v_pk_fma_f32 v[4:5], v[38:39], v[4:5], v[8:9]
	v_pk_fma_f32 v[6:7], v[40:41], v[6:7], v[10:11]
	global_store_dwordx4 v[18:19], v[4:7], off
	v_ashrrev_i32_e32 v161, 31, v160
	v_ashrrev_i32_e32 v163, 31, v162
	v_lshlrev_b64 v[176:177], 2, v[160:161]
	v_lshlrev_b64 v[178:179], 2, v[162:163]
	v_lshl_add_u64 v[180:181], s[54:55], 0, v[176:177]
	v_lshl_add_u64 v[176:177], s[56:57], 0, v[176:177]
	v_lshl_add_u64 v[182:183], s[54:55], 0, v[178:179]
	v_lshl_add_u64 v[178:179], s[56:57], 0, v[178:179]
	global_load_dword v174, v[176:177], off
	global_load_dword v175, v[178:179], off
	global_load_dword v161, v[180:181], off
	global_load_dword v163, v[182:183], off
	global_load_dwordx4 v[4:7], v[16:17], off offset:16
	s_waitcnt vmcnt(0)
	v_pk_fma_f32 v[4:5], v[34:35], v[4:5], v[12:13]
	v_pk_fma_f32 v[6:7], v[36:37], v[6:7], v[14:15]
	global_store_dwordx4 v[18:19], v[4:7], off offset:16
	global_load_dwordx4 v[4:7], v[16:17], off offset:32
	s_nop 0
	global_load_dwordx4 v[8:11], v[18:19], off offset:32
	global_load_dwordx4 v[12:15], v[18:19], off offset:48
	s_waitcnt vmcnt(1)
	v_pk_fma_f32 v[4:5], v[28:29], v[4:5], v[8:9]
	v_pk_fma_f32 v[6:7], v[30:31], v[6:7], v[10:11]
	global_store_dwordx4 v[18:19], v[4:7], off offset:32
	global_load_dwordx4 v[4:7], v[16:17], off offset:48
	s_waitcnt vmcnt(0)
	v_pk_fma_f32 v[4:5], v[26:27], v[4:5], v[12:13]
	v_pk_fma_f32 v[6:7], v[32:33], v[6:7], v[14:15]
	global_store_dwordx4 v[18:19], v[4:7], off offset:48
	s_andn2_b64 exec, exec, s[18:19]
	s_cbranch_execz .LBB0_1067
.LBB0_1061:
	v_ashrrev_i32_e32 v133, 31, v132
	v_mov_b32_e32 v4, v160
	v_mov_b32_e32 v5, v161
	v_mov_b32_e32 v6, v162
	v_mov_b32_e32 v7, v163
	s_mov_b32 s22, 0
	v_mov_b32_e32 v38, 0
	v_mov_b32_e32 v39, v77
	v_mov_b32_e32 v40, 0
	v_mov_b32_e32 v41, v77
	v_mov_b32_e32 v34, 0
	v_mov_b32_e32 v35, v77
	v_mov_b32_e32 v36, 0
	v_mov_b32_e32 v37, v77
	v_mov_b32_e32 v28, 0
	v_mov_b32_e32 v29, v77
	v_mov_b32_e32 v30, 0
	v_mov_b32_e32 v31, v77
	v_mov_b32_e32 v26, 0
	v_mov_b32_e32 v27, v77
	v_mov_b32_e32 v32, 0
	v_lshlrev_b64 v[8:9], 10, v[132:133]
	v_lshlrev_b32_e32 v10, 16, v164
	v_and_b32_e32 v11, 0xffff0000, v164
	v_lshlrev_b32_e32 v12, 16, v165
	v_and_b32_e32 v13, 0xffff0000, v165
	v_lshlrev_b32_e32 v14, 16, v166
	v_and_b32_e32 v15, 0xffff0000, v166
	v_lshlrev_b32_e32 v16, 16, v167
	v_and_b32_e32 v17, 0xffff0000, v167
	v_lshlrev_b32_e32 v18, 16, v168
	v_and_b32_e32 v19, 0xffff0000, v168
	v_lshlrev_b32_e32 v20, 16, v169
	v_and_b32_e32 v21, 0xffff0000, v169
	v_lshlrev_b32_e32 v22, 16, v170
	v_and_b32_e32 v23, 0xffff0000, v170
	v_lshlrev_b32_e32 v24, 16, v171
	v_and_b32_e32 v25, 0xffff0000, v171
	v_mul_f32_e32 v87, v172, v174
	v_mul_f32_e32 v88, v173, v175
	v_mov_b32_e32 v33, v77
	s_branch .LBB0_1063
